# weight transpose: LDS reads of each output group issued together, single wait
# baseline (speedup 1.0000x reference)
; #define LAS __attribute__((address_space(3)))
; __device__ __forceinline__ unsigned cvt_pk_bf16(float lo, float hi) { unsigned r; asm volatile("s_nop 0\n\tv_cvt_pk_bf16_f32 %0, %1, %2" : "=v"(r) : "v"(lo), "v"(hi)); return r; }
; #define LDS_FENCE() asm volatile("s_waitcnt lgkmcnt(0)" ::: "memory")
; __device__ __forceinline__ void tr_item(const float* W, int K, int N, bf16_t* WT, int ldk, int split, int shift, LAS float* scr, int item, int lane) {
;     ...
;     for (int i = 0; i < 16; ++i) { const int kk = i * 4 + rq; tv[i] = okc ? *(const f32x4*)(W + (size_t)(k0 + kk) * N + n0 + c4) : (f32x4){0.f, 0.f, 0.f, 0.f}; }
; #pragma unroll
;     for (int i = 0; i < 16; ++i) { const int kk = i * 4 + rq; LAS float* d = scr + kk * 65 + c4; d[0] = tv[i][0]; d[1] = tv[i][1]; d[2] = tv[i][2]; d[3] = tv[i][3]; }
;     LDS_FENCE();
;     const int c = lane & 7;
; #pragma unroll
;     for (int j = 0; j < 8; ++j) { const int n = (lane >> 3) + 8 * j, ng = n0 + n;
;         if (ng < N) { const LAS float* sp = scr + (8 * c) * 65 + n;
;             u32x4 o; o.x = cvt_pk_bf16(sp[0], sp[65]); o.y = cvt_pk_bf16(sp[130], sp[195]); o.z = cvt_pk_bf16(sp[260], sp[325]); o.w = cvt_pk_bf16(sp[390], sp[455]);
;             const int dr = ng < split ? ng : ng + shift;
;             *(u32x4*)(WT + (size_t)dr * ldk + k0 + 8 * c) = o; } }
.LBB0_42:
	s_or_b64 exec, exec, s[28:29]
	s_waitcnt vmcnt(0)
	ds_write2_b32 v94, v6, v7 offset1:1
	ds_write2_b32 v94, v8, v9 offset0:2 offset1:3
	v_add_u32_e32 v6, 0x410, v94
	ds_write2_b32 v6, v2, v3 offset1:1
	v_add_u32_e32 v2, 0x418, v94
	ds_write2_b32 v2, v4, v5 offset1:1
	v_add_u32_e32 v2, 0x820, v94
	ds_write2_b32 v2, v14, v15 offset1:1
	v_add_u32_e32 v2, 0x828, v94
	ds_write2_b32 v2, v16, v17 offset1:1
	v_add_u32_e32 v2, 0xc30, v94
	ds_write2_b32 v2, v10, v11 offset1:1
	v_add_u32_e32 v2, 0xc38, v94
	ds_write2_b32 v2, v12, v13 offset1:1
	v_add_u32_e32 v2, 0x1040, v94
	ds_write2_b32 v2, v22, v23 offset1:1
	v_add_u32_e32 v2, 0x1048, v94
	ds_write2_b32 v2, v24, v25 offset1:1
	v_add_u32_e32 v2, 0x1450, v94
	ds_write2_b32 v2, v18, v19 offset1:1
	v_add_u32_e32 v2, 0x1458, v94
	ds_write2_b32 v2, v20, v21 offset1:1
	v_add_u32_e32 v2, 0x1860, v94
	ds_write2_b32 v2, v30, v31 offset1:1
	v_add_u32_e32 v2, 0x1868, v94
	ds_write2_b32 v2, v32, v33 offset1:1
	v_add_u32_e32 v2, 0x1c70, v94
	ds_write2_b32 v2, v26, v27 offset1:1
	v_add_u32_e32 v2, 0x1c78, v94
	ds_write2_b32 v2, v28, v29 offset1:1
	v_add_u32_e32 v2, 0x2080, v94
	ds_write2_b32 v2, v38, v39 offset1:1
	v_add_u32_e32 v2, 0x2088, v94
	ds_write2_b32 v2, v40, v41 offset1:1
	v_add_u32_e32 v2, 0x2490, v94
	ds_write2_b32 v2, v34, v35 offset1:1
	v_add_u32_e32 v2, 0x2498, v94
	ds_write2_b32 v2, v36, v37 offset1:1
	v_add_u32_e32 v2, 0x28a0, v94
	ds_write2_b32 v2, v46, v47 offset1:1
	v_add_u32_e32 v2, 0x28a8, v94
	ds_write2_b32 v2, v48, v49 offset1:1
	v_add_u32_e32 v2, 0x2cb0, v94
	ds_write2_b32 v2, v42, v43 offset1:1
	v_add_u32_e32 v2, 0x2cb8, v94
	ds_write2_b32 v2, v44, v45 offset1:1
	v_add_u32_e32 v2, 0x30c0, v94
	ds_write2_b32 v2, v54, v55 offset1:1
	v_add_u32_e32 v2, 0x30c8, v94
	ds_write2_b32 v2, v56, v57 offset1:1
	v_add_u32_e32 v2, 0x34d0, v94
	ds_write2_b32 v2, v50, v51 offset1:1
	v_add_u32_e32 v2, 0x34d8, v94
	ds_write2_b32 v2, v52, v53 offset1:1
	v_add_u32_e32 v2, 0x38e0, v94
	ds_write2_b32 v2, v62, v63 offset1:1
	v_add_u32_e32 v2, 0x38e8, v94
	ds_write2_b32 v2, v64, v65 offset1:1
	v_add_u32_e32 v2, 0x3cf0, v94
	ds_write2_b32 v2, v58, v59 offset1:1
	v_add_u32_e32 v2, 0x3cf8, v94
	ds_write2_b32 v2, v60, v61 offset1:1
	s_waitcnt lgkmcnt(0)
	v_ashrrev_i32_e32 v89, 31, v88
	v_or_b32_e32 v4, v86, v95
	v_lshl_add_u64 v[2:3], v[88:89], 1, v[82:83]
	v_cmp_gt_i32_e64 s[14:15], s33, v4
	s_and_saveexec_b64 s[28:29], s[14:15]
	s_cbranch_execz .LBB0_44
	v_add_u32_e32 v5, 0x400, v96
	v_cmp_gt_i32_e64 s[14:15], s37, v4
	ds_read2_b32 v[6:7], v96 offset1:65
	ds_read2_b32 v[8:9], v96 offset0:130 offset1:195
	ds_read2_b32 v[10:11], v5 offset0:4 offset1:69
	ds_read2_b32 v[12:13], v5 offset0:134 offset1:199
	s_waitcnt lgkmcnt(0)
	s_nop 0
	v_cvt_pk_bf16_f32 v6, v6, v7
	s_nop 0
	v_cvt_pk_bf16_f32 v7, v8, v9
	s_nop 0
	v_cvt_pk_bf16_f32 v8, v10, v11
	s_nop 0
	v_cvt_pk_bf16_f32 v9, v12, v13
	v_cndmask_b32_e64 v5, v106, 0, s[14:15]
	v_add_u32_e32 v4, v5, v4
	v_ashrrev_i32_e32 v5, 31, v4
	v_lshlrev_b64 v[4:5], 12, v[4:5]
	v_lshl_add_u64 v[4:5], v[2:3], 0, v[4:5]
	global_store_dwordx4 v[4:5], v[6:9], off
.LBB0_44:
	s_or_b64 exec, exec, s[28:29]
	v_or_b32_e32 v4, v86, v97
	v_cmp_gt_i32_e64 s[14:15], s33, v4
	s_and_saveexec_b64 s[28:29], s[14:15]
	s_cbranch_execz .LBB0_46
	v_add_u32_e32 v5, 0x400, v96
	v_cmp_gt_i32_e64 s[14:15], s37, v4
	ds_read2_b32 v[6:7], v96 offset0:8 offset1:73
	ds_read2_b32 v[8:9], v96 offset0:138 offset1:203
	ds_read2_b32 v[10:11], v5 offset0:12 offset1:77
	ds_read2_b32 v[12:13], v5 offset0:142 offset1:207
	s_waitcnt lgkmcnt(0)
	s_nop 0
	v_cvt_pk_bf16_f32 v6, v6, v7
	s_nop 0
	v_cvt_pk_bf16_f32 v7, v8, v9
	s_nop 0
	v_cvt_pk_bf16_f32 v8, v10, v11
	s_nop 0
	v_cvt_pk_bf16_f32 v9, v12, v13
	v_cndmask_b32_e64 v5, v106, 0, s[14:15]
	v_add_u32_e32 v4, v5, v4
	v_ashrrev_i32_e32 v5, 31, v4
	v_lshlrev_b64 v[4:5], 12, v[4:5]
	v_lshl_add_u64 v[4:5], v[2:3], 0, v[4:5]
	global_store_dwordx4 v[4:5], v[6:9], off
.LBB0_46:
	s_or_b64 exec, exec, s[28:29]
	v_or_b32_e32 v4, v86, v98
	v_cmp_gt_i32_e64 s[14:15], s33, v4
	s_and_saveexec_b64 s[28:29], s[14:15]
	s_cbranch_execz .LBB0_48
	v_add_u32_e32 v5, 0x400, v96
	v_cmp_gt_i32_e64 s[14:15], s37, v4
	ds_read2_b32 v[6:7], v96 offset0:16 offset1:81
	ds_read2_b32 v[8:9], v96 offset0:146 offset1:211
	ds_read2_b32 v[10:11], v5 offset0:20 offset1:85
	ds_read2_b32 v[12:13], v5 offset0:150 offset1:215
	s_waitcnt lgkmcnt(0)
	s_nop 0
	v_cvt_pk_bf16_f32 v6, v6, v7
	s_nop 0
	v_cvt_pk_bf16_f32 v7, v8, v9
	s_nop 0
	v_cvt_pk_bf16_f32 v8, v10, v11
	s_nop 0
	v_cvt_pk_bf16_f32 v9, v12, v13
	v_cndmask_b32_e64 v5, v106, 0, s[14:15]
	v_add_u32_e32 v4, v5, v4
	v_ashrrev_i32_e32 v5, 31, v4
	v_lshlrev_b64 v[4:5], 12, v[4:5]
	v_lshl_add_u64 v[4:5], v[2:3], 0, v[4:5]
	global_store_dwordx4 v[4:5], v[6:9], off
; #define LAS __attribute__((address_space(3)))
; __device__ __forceinline__ unsigned cvt_pk_bf16(float lo, float hi) { unsigned r; asm volatile("s_nop 0\n\tv_cvt_pk_bf16_f32 %0, %1, %2" : "=v"(r) : "v"(lo), "v"(hi)); return r; }
; __device__ __forceinline__ void tr_item(const float* W, int K, int N, bf16_t* WT, int ldk, int split, int shift, LAS float* scr, int item, int lane) {
;     ...
; #pragma unroll
;     for (int j = 0; j < 8; ++j) { const int n = (lane >> 3) + 8 * j, ng = n0 + n;
;         if (ng < N) { const LAS float* sp = scr + (8 * c) * 65 + n;
;             u32x4 o; o.x = cvt_pk_bf16(sp[0], sp[65]); o.y = cvt_pk_bf16(sp[130], sp[195]); o.z = cvt_pk_bf16(sp[260], sp[325]); o.w = cvt_pk_bf16(sp[390], sp[455]);
;             const int dr = ng < split ? ng : ng + shift;
;             *(u32x4*)(WT + (size_t)dr * ldk + k0 + 8 * c) = o; } }
.LBB0_48:
	s_or_b64 exec, exec, s[28:29]
	v_or_b32_e32 v4, v86, v99
	v_cmp_gt_i32_e64 s[14:15], s33, v4
	s_and_saveexec_b64 s[28:29], s[14:15]
	s_cbranch_execz .LBB0_50
	v_add_u32_e32 v5, 0x400, v96
	v_cmp_gt_i32_e64 s[14:15], s37, v4
	ds_read2_b32 v[6:7], v96 offset0:24 offset1:89
	ds_read2_b32 v[8:9], v96 offset0:154 offset1:219
	ds_read2_b32 v[10:11], v5 offset0:28 offset1:93
	ds_read2_b32 v[12:13], v5 offset0:158 offset1:223
	s_waitcnt lgkmcnt(0)
	s_nop 0
	v_cvt_pk_bf16_f32 v6, v6, v7
	s_nop 0
	v_cvt_pk_bf16_f32 v7, v8, v9
	s_nop 0
	v_cvt_pk_bf16_f32 v8, v10, v11
	s_nop 0
	v_cvt_pk_bf16_f32 v9, v12, v13
	v_cndmask_b32_e64 v5, v106, 0, s[14:15]
	v_add_u32_e32 v4, v5, v4
	v_ashrrev_i32_e32 v5, 31, v4
	v_lshlrev_b64 v[4:5], 12, v[4:5]
	v_lshl_add_u64 v[4:5], v[2:3], 0, v[4:5]
	global_store_dwordx4 v[4:5], v[6:9], off
.LBB0_50:
	s_or_b64 exec, exec, s[28:29]
	v_or_b32_e32 v4, v86, v100
	v_cmp_gt_i32_e64 s[14:15], s33, v4
	s_and_saveexec_b64 s[28:29], s[14:15]
	s_cbranch_execz .LBB0_52
	v_add_u32_e32 v5, 0x400, v96
	v_cmp_gt_i32_e64 s[14:15], s37, v4
	ds_read2_b32 v[6:7], v96 offset0:32 offset1:97
	ds_read2_b32 v[8:9], v96 offset0:162 offset1:227
	ds_read2_b32 v[10:11], v5 offset0:36 offset1:101
	ds_read2_b32 v[12:13], v5 offset0:166 offset1:231
	s_waitcnt lgkmcnt(0)
	s_nop 0
	v_cvt_pk_bf16_f32 v6, v6, v7
	s_nop 0
	v_cvt_pk_bf16_f32 v7, v8, v9
	s_nop 0
	v_cvt_pk_bf16_f32 v8, v10, v11
	s_nop 0
	v_cvt_pk_bf16_f32 v9, v12, v13
	v_cndmask_b32_e64 v5, v106, 0, s[14:15]
	v_add_u32_e32 v4, v5, v4
	v_ashrrev_i32_e32 v5, 31, v4
	v_lshlrev_b64 v[4:5], 12, v[4:5]
	v_lshl_add_u64 v[4:5], v[2:3], 0, v[4:5]
	global_store_dwordx4 v[4:5], v[6:9], off
.LBB0_52:
	s_or_b64 exec, exec, s[28:29]
	v_or_b32_e32 v4, v86, v101
	v_cmp_gt_i32_e64 s[14:15], s33, v4
	s_and_saveexec_b64 s[28:29], s[14:15]
	s_cbranch_execz .LBB0_54
	v_add_u32_e32 v5, 0x400, v96
	v_cmp_gt_i32_e64 s[14:15], s37, v4
	ds_read2_b32 v[6:7], v96 offset0:40 offset1:105
	ds_read2_b32 v[8:9], v96 offset0:170 offset1:235
	ds_read2_b32 v[10:11], v5 offset0:44 offset1:109
	ds_read2_b32 v[12:13], v5 offset0:174 offset1:239
	s_waitcnt lgkmcnt(0)
	s_nop 0
	v_cvt_pk_bf16_f32 v6, v6, v7
	s_nop 0
	v_cvt_pk_bf16_f32 v7, v8, v9
	s_nop 0
	v_cvt_pk_bf16_f32 v8, v10, v11
	s_nop 0
	v_cvt_pk_bf16_f32 v9, v12, v13
	v_cndmask_b32_e64 v5, v106, 0, s[14:15]
	v_add_u32_e32 v4, v5, v4
	v_ashrrev_i32_e32 v5, 31, v4
	v_lshlrev_b64 v[4:5], 12, v[4:5]
	v_lshl_add_u64 v[4:5], v[2:3], 0, v[4:5]
	global_store_dwordx4 v[4:5], v[6:9], off
.LBB0_54:
	s_or_b64 exec, exec, s[28:29]
	v_or_b32_e32 v4, v86, v102
	v_cmp_gt_i32_e64 s[14:15], s33, v4
	s_and_saveexec_b64 s[28:29], s[14:15]
	s_cbranch_execz .LBB0_56
	v_add_u32_e32 v5, 0x400, v96
	v_cmp_gt_i32_e64 s[14:15], s37, v4
	ds_read2_b32 v[6:7], v96 offset0:48 offset1:113
	ds_read2_b32 v[8:9], v96 offset0:178 offset1:243
	ds_read2_b32 v[10:11], v5 offset0:52 offset1:117
	ds_read2_b32 v[12:13], v5 offset0:182 offset1:247
	s_waitcnt lgkmcnt(0)
	s_nop 0
	v_cvt_pk_bf16_f32 v6, v6, v7
	s_nop 0
	v_cvt_pk_bf16_f32 v7, v8, v9
	s_nop 0
	v_cvt_pk_bf16_f32 v8, v10, v11
	s_nop 0
	v_cvt_pk_bf16_f32 v9, v12, v13
	v_cndmask_b32_e64 v5, v106, 0, s[14:15]
	v_add_u32_e32 v4, v5, v4
	v_ashrrev_i32_e32 v5, 31, v4
	v_lshlrev_b64 v[4:5], 12, v[4:5]
	v_lshl_add_u64 v[4:5], v[2:3], 0, v[4:5]
	global_store_dwordx4 v[4:5], v[6:9], off
.LBB0_56:
	s_or_b64 exec, exec, s[28:29]
	v_or_b32_e32 v4, v86, v103
	v_cmp_gt_i32_e64 s[14:15], s33, v4
	s_and_saveexec_b64 s[28:29], s[14:15]
	s_cbranch_execz .LBB0_9
	v_add_u32_e32 v5, 0x400, v96
	v_cmp_gt_i32_e64 s[14:15], s37, v4
	ds_read2_b32 v[6:7], v96 offset0:56 offset1:121
	ds_read2_b32 v[8:9], v96 offset0:186 offset1:251
	ds_read2_b32 v[10:11], v5 offset0:60 offset1:125
	ds_read2_b32 v[12:13], v5 offset0:190 offset1:255
	s_waitcnt lgkmcnt(0)
	s_nop 0
	v_cvt_pk_bf16_f32 v6, v6, v7
	s_nop 0
	v_cvt_pk_bf16_f32 v7, v8, v9
	s_nop 0
	v_cvt_pk_bf16_f32 v8, v10, v11
	s_nop 0
	v_cvt_pk_bf16_f32 v9, v12, v13
	v_cndmask_b32_e64 v5, v106, 0, s[14:15]
	v_add_u32_e32 v4, v5, v4
	v_ashrrev_i32_e32 v5, 31, v4
	v_lshlrev_b64 v[4:5], 12, v[4:5]
	v_lshl_add_u64 v[2:3], v[2:3], 0, v[4:5]
	global_store_dwordx4 v[2:3], v[6:9], off
	s_branch .LBB0_9

; #define LAS __attribute__((address_space(3)))
; __device__ __forceinline__ unsigned cvt_pk_bf16(float lo, float hi) { unsigned r; asm volatile("s_nop 0\n\tv_cvt_pk_bf16_f32 %0, %1, %2" : "=v"(r) : "v"(lo), "v"(hi)); return r; }
; __device__ __forceinline__ void tr_item(const float* W, int K, int N, bf16_t* WT, int ldk, int split, int shift, LAS float* scr, int item, int lane) {
;     ...
;     for (int j = 0; j < 8; ++j) { const int n = (lane >> 3) + 8 * j, ng = n0 + n;
;         if (ng < N) { const LAS float* sp = scr + (8 * c) * 65 + n;
;             u32x4 o; o.x = cvt_pk_bf16(sp[0], sp[65]); o.y = cvt_pk_bf16(sp[130], sp[195]); o.z = cvt_pk_bf16(sp[260], sp[325]); o.w = cvt_pk_bf16(sp[390], sp[455]);
;             const int dr = ng < split ? ng : ng + shift;
;             *(u32x4*)(WT + (size_t)dr * ldk + k0 + 8 * c) = o; } }
.LBB0_107:
	s_or_b64 exec, exec, s[34:35]
	v_add_u32_e32 v4, 56, v4
	v_cmp_gt_i32_e64 s[14:15], s39, v4
	s_and_saveexec_b64 s[34:35], s[14:15]
	s_cbranch_execz .LBB0_60
	v_add_u32_e32 v5, 0x400, v96
	ds_read2_b32 v[6:7], v96 offset0:56 offset1:121
	ds_read2_b32 v[8:9], v96 offset0:186 offset1:251
	ds_read2_b32 v[10:11], v5 offset0:60 offset1:125
	ds_read2_b32 v[12:13], v5 offset0:190 offset1:255
	s_waitcnt lgkmcnt(0)
	s_nop 0
	v_cvt_pk_bf16_f32 v6, v6, v7
	s_nop 0
	v_cvt_pk_bf16_f32 v7, v8, v9
	s_nop 0
	v_cvt_pk_bf16_f32 v8, v10, v11
	s_nop 0
	v_cvt_pk_bf16_f32 v9, v12, v13
	v_ashrrev_i32_e32 v5, 31, v4
	v_lshlrev_b64 v[4:5], 12, v[4:5]
	v_lshl_add_u64 v[2:3], v[2:3], 0, v[4:5]
	global_store_dwordx4 v[2:3], v[6:9], off
	s_branch .LBB0_60

; #define LAS __attribute__((address_space(3)))
; __device__ __forceinline__ unsigned cvt_pk_bf16(float lo, float hi) { unsigned r; asm volatile("s_nop 0\n\tv_cvt_pk_bf16_f32 %0, %1, %2" : "=v"(r) : "v"(lo), "v"(hi)); return r; }
; __device__ __forceinline__ void tr_item(const float* W, int K, int N, bf16_t* WT, int ldk, int split, int shift, LAS float* scr, int item, int lane) {
;     ...
;     for (int j = 0; j < 8; ++j) { const int n = (lane >> 3) + 8 * j, ng = n0 + n;
;         if (ng < N) { const LAS float* sp = scr + (8 * c) * 65 + n;
;             u32x4 o; o.x = cvt_pk_bf16(sp[0], sp[65]); o.y = cvt_pk_bf16(sp[130], sp[195]); o.z = cvt_pk_bf16(sp[260], sp[325]); o.w = cvt_pk_bf16(sp[390], sp[455]);
;             const int dr = ng < split ? ng : ng + shift;
;             *(u32x4*)(WT + (size_t)dr * ldk + k0 + 8 * c) = o; } }
.LBB0_157:
	s_or_b64 exec, exec, s[28:29]
	v_add_u32_e32 v4, 56, v4
	v_cmp_gt_i32_e64 s[14:15], s39, v4
	s_and_saveexec_b64 s[28:29], s[14:15]
	s_cbranch_execz .LBB0_110
	v_add_u32_e32 v5, 0x400, v96
	ds_read2_b32 v[6:7], v96 offset0:56 offset1:121
	ds_read2_b32 v[8:9], v96 offset0:186 offset1:251
	ds_read2_b32 v[10:11], v5 offset0:60 offset1:125
	ds_read2_b32 v[12:13], v5 offset0:190 offset1:255
	s_waitcnt lgkmcnt(0)
	s_nop 0
	v_cvt_pk_bf16_f32 v6, v6, v7
	s_nop 0
	v_cvt_pk_bf16_f32 v7, v8, v9
	s_nop 0
	v_cvt_pk_bf16_f32 v8, v10, v11
	s_nop 0
	v_cvt_pk_bf16_f32 v9, v12, v13
	v_ashrrev_i32_e32 v5, 31, v4
	v_lshlrev_b64 v[4:5], 12, v[4:5]
	v_lshl_add_u64 v[2:3], v[2:3], 0, v[4:5]
	global_store_dwordx4 v[2:3], v[6:9], off
	s_branch .LBB0_110

; #define LAS __attribute__((address_space(3)))
; __device__ __forceinline__ unsigned cvt_pk_bf16(float lo, float hi) { unsigned r; asm volatile("s_nop 0\n\tv_cvt_pk_bf16_f32 %0, %1, %2" : "=v"(r) : "v"(lo), "v"(hi)); return r; }
; __device__ __forceinline__ void tr_item(const float* W, int K, int N, bf16_t* WT, int ldk, int split, int shift, LAS float* scr, int item, int lane) {
;     ...
;     for (int j = 0; j < 8; ++j) { const int n = (lane >> 3) + 8 * j, ng = n0 + n;
;         if (ng < N) { const LAS float* sp = scr + (8 * c) * 65 + n;
;             u32x4 o; o.x = cvt_pk_bf16(sp[0], sp[65]); o.y = cvt_pk_bf16(sp[130], sp[195]); o.z = cvt_pk_bf16(sp[260], sp[325]); o.w = cvt_pk_bf16(sp[390], sp[455]);
;             const int dr = ng < split ? ng : ng + shift;
;             *(u32x4*)(WT + (size_t)dr * ldk + k0 + 8 * c) = o; } }
.LBB0_208:
	s_or_b64 exec, exec, s[28:29]
	v_add_u32_e32 v4, 56, v4
	v_cmp_gt_i32_e64 s[14:15], s43, v4
	s_and_saveexec_b64 s[28:29], s[14:15]
	s_cbranch_execz .LBB0_161
	v_add_u32_e32 v5, 0x400, v96
	ds_read2_b32 v[6:7], v96 offset0:56 offset1:121
	ds_read2_b32 v[8:9], v96 offset0:186 offset1:251
	ds_read2_b32 v[10:11], v5 offset0:60 offset1:125
	ds_read2_b32 v[12:13], v5 offset0:190 offset1:255
	s_waitcnt lgkmcnt(0)
	s_nop 0
	v_cvt_pk_bf16_f32 v6, v6, v7
	s_nop 0
	v_cvt_pk_bf16_f32 v7, v8, v9
	s_nop 0
	v_cvt_pk_bf16_f32 v8, v10, v11
	s_nop 0
	v_cvt_pk_bf16_f32 v9, v12, v13
	v_ashrrev_i32_e32 v5, 31, v4
	v_lshlrev_b64 v[4:5], 10, v[4:5]
	v_lshl_add_u64 v[2:3], v[2:3], 0, v[4:5]
	global_store_dwordx4 v[2:3], v[6:9], off
	s_branch .LBB0_161

; #define LAS __attribute__((address_space(3)))
; __device__ __forceinline__ unsigned cvt_pk_bf16(float lo, float hi) { unsigned r; asm volatile("s_nop 0\n\tv_cvt_pk_bf16_f32 %0, %1, %2" : "=v"(r) : "v"(lo), "v"(hi)); return r; }
; __device__ __forceinline__ void tr_item(const float* W, int K, int N, bf16_t* WT, int ldk, int split, int shift, LAS float* scr, int item, int lane) {
;     ...
;     for (int j = 0; j < 8; ++j) { const int n = (lane >> 3) + 8 * j, ng = n0 + n;
;         if (ng < N) { const LAS float* sp = scr + (8 * c) * 65 + n;
;             u32x4 o; o.x = cvt_pk_bf16(sp[0], sp[65]); o.y = cvt_pk_bf16(sp[130], sp[195]); o.z = cvt_pk_bf16(sp[260], sp[325]); o.w = cvt_pk_bf16(sp[390], sp[455]);
;             const int dr = ng < split ? ng : ng + shift;
;             *(u32x4*)(WT + (size_t)dr * ldk + k0 + 8 * c) = o; } }
.LBB0_259:
	s_or_b64 exec, exec, s[30:31]
	v_add_u32_e32 v4, 56, v4
	v_cmp_gt_i32_e64 s[14:15], s4, v4
	s_and_saveexec_b64 s[30:31], s[14:15]
	s_cbranch_execz .LBB0_212
	v_add_u32_e32 v5, 0x400, v96
	ds_read2_b32 v[6:7], v96 offset0:56 offset1:121
	ds_read2_b32 v[8:9], v96 offset0:186 offset1:251
	ds_read2_b32 v[10:11], v5 offset0:60 offset1:125
	ds_read2_b32 v[12:13], v5 offset0:190 offset1:255
	s_waitcnt lgkmcnt(0)
	s_nop 0
	v_cvt_pk_bf16_f32 v6, v6, v7
	s_nop 0
	v_cvt_pk_bf16_f32 v7, v8, v9
	s_nop 0
	v_cvt_pk_bf16_f32 v8, v10, v11
	s_nop 0
	v_cvt_pk_bf16_f32 v9, v12, v13
	v_ashrrev_i32_e32 v5, 31, v4
	v_lshlrev_b64 v[4:5], 9, v[4:5]
	v_lshl_add_u64 v[2:3], v[2:3], 0, v[4:5]
	global_store_dwordx4 v[2:3], v[6:9], off
	s_branch .LBB0_212
